# neighbourhood attention: row sums via 16x16x32 bf16 MFMAs with the 0/1 selection-matrix A operand into a 4-register accumulator (half the MFMA passes of the 32x32x16 ones form, same instruction count)
# speedup vs baseline: 1.0173x; 1.0016x over previous
.LBB0_527:
	v_and_b32_e32 v0, 0xc0, v6
	v_lshlrev_b32_e32 v4, 5, v4
	v_readlane_b32 s0, v254, 6
	v_and_b32_e32 v4, 32, v4
	v_lshl_or_b32 v0, v2, 8, v0
	s_add_i32 s0, s10, s0
	v_or3_b32 v238, v0, v4, v5
	v_or_b32_e32 v0, s0, v7
	v_add_u32_e32 v0, -4, v0
	v_sub_co_u32_e64 v4, s[8:9], s0, 4
	v_min_u32_e32 v0, 56, v0
	v_readfirstlane_b32 s1, v4
	v_cndmask_b32_e64 v239, v0, 0, s[8:9]
	s_min_u32 s68, s1, 56
	v_sub_co_u32_e64 v0, s[0:1], s0, 3
	s_nop 0
	v_readfirstlane_b32 s13, v0
	v_lshrrev_b32_e32 v0, 1, v3
	s_min_u32 s13, s13, 56
	v_bfe_u32 v3, v3, 1, 3
	v_add_u16_e32 v4, s12, v8
	v_bitop3_b32 v0, v2, v0, 7 bitop3:0x78
	s_add_i32 s69, s34, 4
	v_lshrrev_b16_e32 v4, 1, v4
	s_add_i32 s13, s13, 7
	v_lshlrev_b32_e32 v241, 4, v0
	v_or_b32_e32 v0, 2, v2
	v_bitop3_b32 v5, v2, v3, 2 bitop3:0x36
	s_and_b64 s[0:1], s[0:1], exec
	v_lshlrev_b32_e32 v242, 4, v5
	v_or_b32_e32 v5, 4, v2
	v_bitop3_b32 v6, v2, v3, 4 bitop3:0x36
	v_bitop3_b32 v0, v4, v0, 7 bitop3:0x6c
	v_lshlrev_b32_e32 v243, 4, v6
	v_or_b32_e32 v6, 6, v2
	v_lshlrev_b32_e32 v246, 4, v0
	v_bitop3_b32 v0, v4, v5, 7 bitop3:0x6c
	v_readlane_b32 s0, v254, 34
	s_cselect_b32 s74, 7, s13
	v_lshlrev_b32_e32 v247, 4, v0
	v_bitop3_b32 v0, v4, v6, 7 bitop3:0x6c
	s_add_i32 s0, s0, s31
	v_bitop3_b32 v3, v2, v3, 6 bitop3:0x36
	v_bitop3_b32 v2, v4, v2, 7 bitop3:0x6c
	v_lshlrev_b32_e32 v248, 4, v0
	v_sub_u32_e32 v0, s0, v7
	v_mov_b32_e32 v14, v1
	v_mov_b32_e32 v15, v1
	v_add_lshl_u32 v237, s12, v8, 7
	v_add_u32_e32 v210, 0, v9
	v_lshlrev_b32_e32 v244, 4, v3
	v_lshlrev_b32_e32 v245, 4, v2
	s_sub_i32 s86, s31, s11
	v_subrev_u32_e32 v249, s10, v0
	v_mov_b32_e32 v0, v1
	v_mov_b32_e32 v2, v1
	v_mov_b32_e32 v3, v1
	v_mov_b32_e32 v4, v1
	v_mov_b32_e32 v5, v1
	v_mov_b32_e32 v6, v1
	v_mov_b32_e32 v7, v1
	v_mov_b32_e32 v8, v1
	v_mov_b32_e32 v9, v1
	v_mov_b32_e32 v10, v1
	v_mov_b32_e32 v11, v1
	v_mov_b32_e32 v12, v1
	v_mov_b32_e32 v13, v1
	v_mov_b64_e32 v[30:31], v[14:15]
	v_mov_b64_e32 v[46:47], v[14:15]
	v_mov_b64_e32 v[62:63], v[14:15]
	v_mov_b64_e32 v[78:79], v[14:15]
	s_movk_i32 s50, 0xc0
	s_mov_b32 s51, 0
	s_lshl_b32 s75, s12, 6
	v_add_u32_e32 v240, 7, v239
	s_mov_b32 s83, 2
	s_add_i32 s86, s86, -4
	s_mov_b64 s[46:47], 0
	v_mov_b32_e32 v212, 0
	v_mov_b64_e32 v[28:29], v[12:13]
	v_mov_b64_e32 v[26:27], v[10:11]
	v_mov_b64_e32 v[24:25], v[8:9]
	v_mov_b64_e32 v[22:23], v[6:7]
	v_mov_b64_e32 v[20:21], v[4:5]
	v_mov_b64_e32 v[18:19], v[2:3]
	v_mov_b64_e32 v[16:17], v[0:1]
	v_mov_b64_e32 v[44:45], v[12:13]
	v_mov_b64_e32 v[42:43], v[10:11]
	v_mov_b64_e32 v[40:41], v[8:9]
	v_mov_b64_e32 v[38:39], v[6:7]
	v_mov_b64_e32 v[36:37], v[4:5]
	v_mov_b64_e32 v[34:35], v[2:3]
	v_mov_b64_e32 v[32:33], v[0:1]
	v_mov_b64_e32 v[60:61], v[12:13]
	v_mov_b64_e32 v[58:59], v[10:11]
	v_mov_b64_e32 v[56:57], v[8:9]
	v_mov_b64_e32 v[54:55], v[6:7]
	v_mov_b64_e32 v[52:53], v[4:5]
	v_mov_b64_e32 v[50:51], v[2:3]
	v_mov_b64_e32 v[48:49], v[0:1]
	v_mov_b64_e32 v[76:77], v[12:13]
	v_mov_b64_e32 v[74:75], v[10:11]
	v_mov_b64_e32 v[72:73], v[8:9]
	v_mov_b64_e32 v[70:71], v[6:7]
	v_mov_b64_e32 v[68:69], v[4:5]
	v_mov_b64_e32 v[66:67], v[2:3]
	v_mov_b64_e32 v[64:65], v[0:1]
	v_mbcnt_lo_u32_b32 v116, -1, 0
	v_mbcnt_hi_u32_b32 v116, -1, v116
	v_lshrrev_b32_e32 v117, 4, v116
	v_lshrrev_b32_e32 v116, 2, v116
	v_xor_b32_e32 v116, v116, v117
	v_and_b32_e32 v116, 1, v116
	v_add_u32_e32 v116, -1, v116
	v_and_b32_e32 v116, s60, v116
	v_mov_b32_e32 v117, v116
	v_mov_b32_e32 v118, v116
	v_mov_b32_e32 v119, v116
	s_nop 0
	s_nop 0
	s_nop 0
	s_nop 0
	s_nop 0
	s_nop 0
	s_nop 0

.Lna_547:
	v_exp_f32_e32 v15, v144
	v_exp_f32_e32 v144, v128
	v_exp_f32_e32 v128, v145
	v_exp_f32_e32 v129, v129
	v_exp_f32_e32 v145, v146
	v_exp_f32_e32 v130, v130
	v_exp_f32_e32 v146, v147
	v_exp_f32_e32 v131, v131
	v_exp_f32_e32 v147, v148
	v_exp_f32_e32 v148, v132
	v_exp_f32_e32 v149, v149
	v_exp_f32_e32 v218, v133
	v_exp_f32_e32 v150, v150
	v_exp_f32_e32 v219, v134
	v_exp_f32_e32 v151, v151
	v_exp_f32_e32 v220, v135
	v_exp_f32_e32 v132, v152
	v_exp_f32_e32 v133, v136
	v_exp_f32_e32 v134, v153
	v_exp_f32_e32 v135, v137
	v_exp_f32_e32 v137, v154
	v_exp_f32_e32 v138, v138
	v_exp_f32_e32 v152, v155
	v_exp_f32_e32 v139, v139
	v_exp_f32_e32 v153, v156
	v_exp_f32_e32 v154, v140
	v_exp_f32_e32 v155, v157
	v_exp_f32_e32 v156, v141
	v_exp_f32_e32 v157, v158
	v_exp_f32_e32 v158, v142
	v_exp_f32_e32 v159, v159
	v_exp_f32_e32 v143, v143
	v_cvt_pk_bf16_f32 v128, v15, v128
	v_cvt_pk_bf16_f32 v132, v132, v134
	v_cvt_pk_bf16_f32 v136, v144, v129
	v_cvt_pk_bf16_f32 v140, v133, v135
	v_cvt_pk_bf16_f32 v129, v145, v146
	v_cvt_pk_bf16_f32 v133, v137, v152
	v_cvt_pk_bf16_f32 v137, v130, v131
	v_cvt_pk_bf16_f32 v141, v138, v139
	v_cvt_pk_bf16_f32 v130, v147, v149
	v_cvt_pk_bf16_f32 v134, v153, v155
	v_cvt_pk_bf16_f32 v138, v148, v218
	v_cvt_pk_bf16_f32 v142, v154, v156
	v_cvt_pk_bf16_f32 v131, v150, v151
	v_cvt_pk_bf16_f32 v135, v157, v159
	v_cvt_pk_bf16_f32 v139, v219, v220
	v_cvt_pk_bf16_f32 v143, v158, v143
	ds_read_b64_tr_b16 v[144:145], v0 offset:12288
	ds_read_b64_tr_b16 v[146:147], v0 offset:12800
	ds_read_b64_tr_b16 v[148:149], v0 offset:13312
	ds_read_b64_tr_b16 v[150:151], v0 offset:13824
	ds_read_b64_tr_b16 v[152:153], v0 offset:14336
	ds_read_b64_tr_b16 v[154:155], v0 offset:14848
	ds_read_b64_tr_b16 v[156:157], v0 offset:15360
	ds_read_b64_tr_b16 v[158:159], v0 offset:15872
	s_setprio 1
	s_waitcnt lgkmcnt(8)
	v_mfma_f32_32x32x16_bf16 v[16:31], v[192:195], v[128:131], v[16:31]
	v_mfma_f32_32x32x16_bf16 v[16:31], v[10:13], v[132:135], v[16:31]
	v_mfma_f32_32x32x16_bf16 v[16:31], v[6:9], v[136:139], v[16:31]
	v_mfma_f32_32x32x16_bf16 v[16:31], v[2:5], v[140:143], v[16:31]
	v_mfma_f32_16x16x32_bf16 v[48:51], v[116:119], v[128:131], v[48:51]
	s_waitcnt lgkmcnt(6)
	v_mfma_f32_32x32x16_bf16 v[32:47], v[144:147], v[128:131], v[32:47]
	v_mfma_f32_16x16x32_bf16 v[48:51], v[116:119], v[132:135], v[48:51]
	s_waitcnt lgkmcnt(4)
	v_mfma_f32_32x32x16_bf16 v[32:47], v[148:151], v[132:135], v[32:47]
	v_mfma_f32_16x16x32_bf16 v[48:51], v[116:119], v[136:139], v[48:51]
	s_waitcnt lgkmcnt(2)
	v_mfma_f32_32x32x16_bf16 v[32:47], v[152:155], v[136:139], v[32:47]
	v_mfma_f32_16x16x32_bf16 v[48:51], v[116:119], v[140:143], v[48:51]
	s_waitcnt lgkmcnt(0)
	v_mfma_f32_32x32x16_bf16 v[32:47], v[156:159], v[140:143], v[32:47]
	s_setprio 0
	s_branch .Lna_next

.Lna_541:
	v_exp_f32_e32 v0, v14
	v_exp_f32_e32 v14, v15
	v_exp_f32_e32 v15, v80
	v_exp_f32_e32 v81, v81
	v_exp_f32_e32 v82, v82
	v_exp_f32_e32 v83, v83
	v_exp_f32_e32 v94, v84
	v_exp_f32_e32 v95, v85
	v_exp_f32_e32 v84, v86
	v_exp_f32_e32 v85, v87
	v_exp_f32_e32 v86, v88
	v_exp_f32_e32 v87, v89
	v_exp_f32_e32 v88, v90
	v_exp_f32_e32 v89, v91
	v_exp_f32_e32 v90, v92
	v_exp_f32_e32 v91, v93
	v_cvt_pk_bf16_f32 v80, v0, v14
	v_cvt_pk_bf16_f32 v84, v84, v85
	v_cvt_pk_bf16_f32 v81, v15, v81
	v_cvt_pk_bf16_f32 v85, v86, v87
	v_cvt_pk_bf16_f32 v82, v82, v83
	v_cvt_pk_bf16_f32 v86, v88, v89
	v_cvt_pk_bf16_f32 v83, v94, v95
	v_cvt_pk_bf16_f32 v87, v90, v91
	s_setprio 1
	s_waitcnt lgkmcnt(0)
	v_mfma_f32_32x32x16_bf16 v[32:47], v[10:13], v[80:83], v[32:47]
	v_mfma_f32_32x32x16_bf16 v[32:47], v[6:9], v[84:87], v[32:47]
	v_mfma_f32_32x32x16_bf16 v[16:31], v[96:99], v[80:83], v[16:31]
	v_mfma_f32_16x16x32_bf16 v[48:51], v[116:119], v[80:83], v[48:51]
	v_mfma_f32_16x16x32_bf16 v[48:51], v[116:119], v[84:87], v[48:51]
	v_mfma_f32_32x32x16_bf16 v[16:31], v[2:5], v[84:87], v[16:31]
	s_setprio 0
